# adaLN/bias GEMV loops: 16 weight-row loads per block now issued together with counted vmcnt waits (were one load in flight with vmcnt(0) each); plus pipelined single-path MLA loop with hidden row-max,
# speedup vs baseline: 1.0271x; 1.0142x over previous
.LBB0_53:
	v_lshl_add_u64 v[22:23], v[20:21], 0, s[12:13]
	global_load_dword v100, v[22:23], off
	v_mov_b32_e32 v140, v22
	v_mov_b32_e32 v141, v23
	v_add_co_u32_e32 v140, vcc, 0x1e80, v140
	s_nop 1
	v_addc_co_u32_e32 v141, vcc, 0, v141, vcc
	global_load_dword v102, v[140:141], off
	v_add_co_u32_e32 v140, vcc, 0x1e80, v140
	s_nop 1
	v_addc_co_u32_e32 v141, vcc, 0, v141, vcc
	global_load_dword v104, v[140:141], off
	v_add_co_u32_e32 v140, vcc, 0x1e80, v140
	s_nop 1
	v_addc_co_u32_e32 v141, vcc, 0, v141, vcc
	global_load_dword v106, v[140:141], off
	v_add_co_u32_e32 v140, vcc, 0x1e80, v140
	s_nop 1
	v_addc_co_u32_e32 v141, vcc, 0, v141, vcc
	global_load_dword v108, v[140:141], off
	v_add_co_u32_e32 v140, vcc, 0x1e80, v140
	s_nop 1
	v_addc_co_u32_e32 v141, vcc, 0, v141, vcc
	global_load_dword v110, v[140:141], off
	v_add_co_u32_e32 v140, vcc, 0x1e80, v140
	s_nop 1
	v_addc_co_u32_e32 v141, vcc, 0, v141, vcc
	global_load_dword v112, v[140:141], off
	v_add_co_u32_e32 v140, vcc, 0x1e80, v140
	s_nop 1
	v_addc_co_u32_e32 v141, vcc, 0, v141, vcc
	global_load_dword v114, v[140:141], off
	v_add_co_u32_e32 v140, vcc, 0x1e80, v140
	s_nop 1
	v_addc_co_u32_e32 v141, vcc, 0, v141, vcc
	global_load_dword v116, v[140:141], off
	v_add_co_u32_e32 v140, vcc, 0x1e80, v140
	s_nop 1
	v_addc_co_u32_e32 v141, vcc, 0, v141, vcc
	global_load_dword v118, v[140:141], off
	v_add_co_u32_e32 v140, vcc, 0x1e80, v140
	s_nop 1
	v_addc_co_u32_e32 v141, vcc, 0, v141, vcc
	global_load_dword v120, v[140:141], off
	v_add_co_u32_e32 v140, vcc, 0x1e80, v140
	s_nop 1
	v_addc_co_u32_e32 v141, vcc, 0, v141, vcc
	global_load_dword v122, v[140:141], off
	v_add_co_u32_e32 v140, vcc, 0x1e80, v140
	s_nop 1
	v_addc_co_u32_e32 v141, vcc, 0, v141, vcc
	global_load_dword v124, v[140:141], off
	v_add_co_u32_e32 v140, vcc, 0x1e80, v140
	s_nop 1
	v_addc_co_u32_e32 v141, vcc, 0, v141, vcc
	global_load_dword v126, v[140:141], off
	v_add_co_u32_e32 v140, vcc, 0x1e80, v140
	s_nop 1
	v_addc_co_u32_e32 v141, vcc, 0, v141, vcc
	global_load_dword v128, v[140:141], off
	v_add_co_u32_e32 v140, vcc, 0x1e80, v140
	s_nop 1
	v_addc_co_u32_e32 v141, vcc, 0, v141, vcc
	global_load_dword v130, v[140:141], off
	ds_read_b128 v[28:31], v27
	ds_read_b128 v[8:11], v27 offset:16
	ds_read_b128 v[4:7], v27 offset:32
	ds_read_b128 v[0:3], v27 offset:48
	ds_read_b128 v[32:35], v27 offset:4096
	s_waitcnt lgkmcnt(4)
	v_mov_b32_e32 v36, v28
	s_movk_i32 s9, 0x3000
	s_add_u32 s12, s12, 0x1e800
	s_addc_u32 s13, s13, 0
	s_waitcnt lgkmcnt(0)
	v_mov_b32_e32 v37, v32
	v_mov_b32_e32 v32, v29
	s_cmp_lg_u32 s12, 0x7a000
	s_waitcnt vmcnt(15)
	v_pk_fma_f32 v[18:19], v[100:101], v[36:37], v[18:19] op_sel_hi:[0,1,1]
	ds_read_b128 v[36:39], v27 offset:8192
	ds_read_b128 v[50:53], v27 offset:12288
	s_waitcnt lgkmcnt(1)
	v_mov_b32_e32 v62, v36
	s_waitcnt lgkmcnt(0)
	v_mov_b32_e32 v63, v50
	v_pk_fma_f32 v[16:17], v[100:101], v[62:63], v[16:17] op_sel_hi:[0,1,1]
	ds_read_b128 v[62:65], v27 offset:16384
	ds_read_b128 v[66:69], v27 offset:20480
	v_mov_b32_e32 v50, v37
	s_waitcnt lgkmcnt(1)
	v_mov_b32_e32 v70, v62
	s_waitcnt lgkmcnt(0)
	v_mov_b32_e32 v71, v66
	v_pk_fma_f32 v[78:79], v[100:101], v[70:71], v[14:15] op_sel_hi:[0,1,1]
	ds_read_b128 v[70:73], v27 offset:24576
	ds_read_b128 v[74:77], v27 offset:28672
	v_mov_b32_e32 v66, v63
	s_waitcnt lgkmcnt(1)
	v_mov_b32_e32 v14, v70
	s_waitcnt lgkmcnt(0)
	v_mov_b32_e32 v15, v74
	v_pk_fma_f32 v[80:81], v[100:101], v[14:15], v[12:13] op_sel_hi:[0,1,1]
	ds_read_b128 v[12:15], v27 offset:32768
	v_mov_b32_e32 v74, v71
	s_waitcnt lgkmcnt(0)
	v_fmac_f32_e32 v26, v100, v12
	s_waitcnt vmcnt(14)
	v_pk_fma_f32 v[18:19], v[102:103], v[32:33], v[18:19] op_sel_hi:[0,1,1]
	v_pk_fma_f32 v[16:17], v[102:103], v[50:51], v[16:17] op_sel_hi:[0,1,1]
	v_pk_fma_f32 v[24:25], v[102:103], v[66:67], v[78:79] op_sel_hi:[0,1,1]
	v_pk_fma_f32 v[28:29], v[102:103], v[74:75], v[80:81] op_sel_hi:[0,1,1]
	v_fmac_f32_e32 v26, v102, v13
	v_mov_b32_e32 v32, v30
	s_nop 0
	v_mov_b32_e32 v33, v34
	s_movk_i32 s9, 0x5000
	v_mov_b32_e32 v34, v31
	s_waitcnt vmcnt(13)
	v_pk_fma_f32 v[18:19], v[104:105], v[32:33], v[18:19] op_sel_hi:[0,1,1]
	v_mov_b32_e32 v32, v38
	v_mov_b32_e32 v33, v52
	v_pk_fma_f32 v[16:17], v[104:105], v[32:33], v[16:17] op_sel_hi:[0,1,1]
	v_mov_b32_e32 v32, v64
	v_mov_b32_e32 v33, v68
	v_pk_fma_f32 v[32:33], v[104:105], v[32:33], v[24:25] op_sel_hi:[0,1,1]
	v_mov_b32_e32 v24, v72
	v_mov_b32_e32 v25, v76
	v_pk_fma_f32 v[28:29], v[104:105], v[24:25], v[28:29] op_sel_hi:[0,1,1]
	v_fmac_f32_e32 v26, v104, v14
	v_mov_b32_e32 v52, v39
	s_nop 0
	v_mov_b32_e32 v68, v65
	v_mov_b32_e32 v76, v73
	s_movk_i32 s9, 0x7000
	s_waitcnt vmcnt(12)
	v_pk_fma_f32 v[24:25], v[106:107], v[34:35], v[18:19] op_sel_hi:[0,1,1]
	v_pk_fma_f32 v[18:19], v[106:107], v[52:53], v[16:17] op_sel_hi:[0,1,1]
	v_pk_fma_f32 v[16:17], v[106:107], v[68:69], v[32:33] op_sel_hi:[0,1,1]
	v_pk_fma_f32 v[12:13], v[106:107], v[76:77], v[28:29] op_sel_hi:[0,1,1]
	v_fmac_f32_e32 v26, v106, v15
	ds_read_b128 v[28:31], v27 offset:4112
	s_nop 0
	v_mov_b32_e32 v32, v8
	s_waitcnt lgkmcnt(0)
	v_mov_b32_e32 v33, v28
	s_mov_b32 s9, 0x9000
	v_mov_b32_e32 v28, v9
	s_waitcnt vmcnt(11)
	v_pk_fma_f32 v[24:25], v[108:109], v[32:33], v[24:25] op_sel_hi:[0,1,1]
	ds_read_b128 v[32:35], v27 offset:8208
	ds_read_b128 v[36:39], v27 offset:12304
	s_waitcnt lgkmcnt(1)
	v_mov_b32_e32 v50, v32
	s_waitcnt lgkmcnt(0)
	v_mov_b32_e32 v51, v36
	v_pk_fma_f32 v[74:75], v[108:109], v[50:51], v[18:19] op_sel_hi:[0,1,1]
	ds_read_b128 v[50:53], v27 offset:16400
	ds_read_b128 v[62:65], v27 offset:20496
	v_mov_b32_e32 v36, v33
	s_waitcnt lgkmcnt(1)
	v_mov_b32_e32 v18, v50
	s_waitcnt lgkmcnt(0)
	v_mov_b32_e32 v19, v62
	v_pk_fma_f32 v[76:77], v[108:109], v[18:19], v[16:17] op_sel_hi:[0,1,1]
	ds_read_b128 v[16:19], v27 offset:24592
	ds_read_b128 v[66:69], v27 offset:28688
	v_mov_b32_e32 v62, v51
	s_waitcnt lgkmcnt(1)
	v_mov_b32_e32 v70, v16
	s_waitcnt lgkmcnt(0)
	v_mov_b32_e32 v71, v66
	v_pk_fma_f32 v[12:13], v[108:109], v[70:71], v[12:13] op_sel_hi:[0,1,1]
	ds_read_b128 v[70:73], v27 offset:32784
	v_mov_b32_e32 v66, v17
	v_mov_b32_e32 v16, v10
	v_mov_b32_e32 v17, v30
	v_mov_b32_e32 v30, v11
	s_waitcnt lgkmcnt(0)
	v_fmac_f32_e32 v26, v108, v70
	s_mov_b32 s9, 0xb000
	s_nop 0
	s_waitcnt vmcnt(10)
	v_pk_fma_f32 v[14:15], v[110:111], v[28:29], v[24:25] op_sel_hi:[0,1,1]
	v_pk_fma_f32 v[24:25], v[110:111], v[36:37], v[74:75] op_sel_hi:[0,1,1]
	v_pk_fma_f32 v[28:29], v[110:111], v[62:63], v[76:77] op_sel_hi:[0,1,1]
	v_pk_fma_f32 v[12:13], v[110:111], v[66:67], v[12:13] op_sel_hi:[0,1,1]
	v_fmac_f32_e32 v26, v110, v71
	s_mov_b32 s9, 0xd000
	s_nop 0
	s_waitcnt vmcnt(9)
	v_pk_fma_f32 v[14:15], v[112:113], v[16:17], v[14:15] op_sel_hi:[0,1,1]
	v_mov_b32_e32 v16, v34
	v_mov_b32_e32 v17, v38
	v_pk_fma_f32 v[16:17], v[112:113], v[16:17], v[24:25] op_sel_hi:[0,1,1]
	v_mov_b32_e32 v24, v52
	v_mov_b32_e32 v25, v64
	v_pk_fma_f32 v[24:25], v[112:113], v[24:25], v[28:29] op_sel_hi:[0,1,1]
	v_mov_b32_e32 v28, v18
	v_mov_b32_e32 v29, v68
	v_pk_fma_f32 v[12:13], v[112:113], v[28:29], v[12:13] op_sel_hi:[0,1,1]
	v_fmac_f32_e32 v26, v112, v72
	v_mov_b32_e32 v38, v35
	s_nop 0
	v_mov_b32_e32 v64, v53
	v_mov_b32_e32 v68, v19
	s_mov_b32 s9, 0xf000
	s_waitcnt vmcnt(8)
	v_pk_fma_f32 v[14:15], v[114:115], v[30:31], v[14:15] op_sel_hi:[0,1,1]
	v_pk_fma_f32 v[28:29], v[114:115], v[38:39], v[16:17] op_sel_hi:[0,1,1]
	v_pk_fma_f32 v[24:25], v[114:115], v[64:65], v[24:25] op_sel_hi:[0,1,1]
	v_pk_fma_f32 v[62:63], v[114:115], v[68:69], v[12:13] op_sel_hi:[0,1,1]
	v_fmac_f32_e32 v26, v114, v73
	v_mov_b32_e32 v12, v4
	s_nop 0
	ds_read_b128 v[8:11], v27 offset:4128
	s_mov_b32 s9, 0x11000
	s_waitcnt lgkmcnt(0)
	v_mov_b32_e32 v13, v8
	v_mov_b32_e32 v8, v5
	s_waitcnt vmcnt(7)
	v_pk_fma_f32 v[68:69], v[116:117], v[12:13], v[14:15] op_sel_hi:[0,1,1]
	ds_read_b128 v[12:15], v27 offset:8224
	ds_read_b128 v[16:19], v27 offset:12320
	s_waitcnt lgkmcnt(1)
	v_mov_b32_e32 v30, v12
	s_waitcnt lgkmcnt(0)
	v_mov_b32_e32 v31, v16
	v_pk_fma_f32 v[70:71], v[116:117], v[30:31], v[28:29] op_sel_hi:[0,1,1]
	ds_read_b128 v[28:31], v27 offset:16416
	ds_read_b128 v[32:35], v27 offset:20512
	v_mov_b32_e32 v16, v13
	s_waitcnt lgkmcnt(1)
	v_mov_b32_e32 v36, v28
	s_waitcnt lgkmcnt(0)
	v_mov_b32_e32 v37, v32
	v_pk_fma_f32 v[24:25], v[116:117], v[36:37], v[24:25] op_sel_hi:[0,1,1]
	ds_read_b128 v[36:39], v27 offset:24608
	ds_read_b128 v[50:53], v27 offset:28704
	v_mov_b32_e32 v32, v29
	v_mov_b32_e32 v28, v6
	v_mov_b32_e32 v29, v10
	s_waitcnt lgkmcnt(1)
	v_mov_b32_e32 v64, v36
	s_waitcnt lgkmcnt(0)
	v_mov_b32_e32 v65, v50
	v_pk_fma_f32 v[72:73], v[116:117], v[64:65], v[62:63] op_sel_hi:[0,1,1]
	ds_read_b128 v[62:65], v27 offset:32800
	v_mov_b32_e32 v50, v37
	v_mov_b32_e32 v10, v7
	s_waitcnt lgkmcnt(0)
	v_fmac_f32_e32 v26, v116, v62
	s_mov_b32 s9, 0x13000
	s_nop 0
	s_waitcnt vmcnt(6)
	v_pk_fma_f32 v[8:9], v[118:119], v[8:9], v[68:69] op_sel_hi:[0,1,1]
	v_pk_fma_f32 v[12:13], v[118:119], v[16:17], v[70:71] op_sel_hi:[0,1,1]
	v_pk_fma_f32 v[16:17], v[118:119], v[32:33], v[24:25] op_sel_hi:[0,1,1]
	v_pk_fma_f32 v[24:25], v[118:119], v[50:51], v[72:73] op_sel_hi:[0,1,1]
	v_fmac_f32_e32 v26, v118, v63
	s_mov_b32 s9, 0x16000
	s_nop 0
	s_waitcnt vmcnt(5)
	v_pk_fma_f32 v[8:9], v[120:121], v[28:29], v[8:9] op_sel_hi:[0,1,1]
	v_mov_b32_e32 v28, v14
	v_mov_b32_e32 v29, v18
	v_pk_fma_f32 v[28:29], v[120:121], v[28:29], v[12:13] op_sel_hi:[0,1,1]
	v_mov_b32_e32 v12, v30
	v_mov_b32_e32 v13, v34
	v_pk_fma_f32 v[16:17], v[120:121], v[12:13], v[16:17] op_sel_hi:[0,1,1]
	v_mov_b32_e32 v12, v38
	v_mov_b32_e32 v13, v52
	v_pk_fma_f32 v[24:25], v[120:121], v[12:13], v[24:25] op_sel_hi:[0,1,1]
	v_fmac_f32_e32 v26, v120, v64
	v_mov_b32_e32 v18, v15
	s_nop 0
	v_mov_b32_e32 v34, v31
	v_mov_b32_e32 v52, v39
	s_waitcnt vmcnt(4)
	v_pk_fma_f32 v[12:13], v[122:123], v[10:11], v[8:9] op_sel_hi:[0,1,1]
	v_pk_fma_f32 v[10:11], v[122:123], v[18:19], v[28:29] op_sel_hi:[0,1,1]
	v_pk_fma_f32 v[8:9], v[122:123], v[34:35], v[16:17] op_sel_hi:[0,1,1]
	v_pk_fma_f32 v[4:5], v[122:123], v[52:53], v[24:25] op_sel_hi:[0,1,1]
	v_fmac_f32_e32 v26, v122, v65
	ds_read_b128 v[14:17], v27 offset:4144
	s_nop 0
	ds_read_b128 v[28:31], v27 offset:8240
	ds_read_b128 v[32:35], v27 offset:12336
	v_mov_b32_e32 v18, v0
	s_waitcnt lgkmcnt(2)
	v_mov_b32_e32 v19, v14
	v_mov_b32_e32 v14, v1
	s_mov_b32 s9, 0x1a000
	s_waitcnt vmcnt(3)
	v_pk_fma_f32 v[18:19], v[124:125], v[18:19], v[12:13] op_sel_hi:[0,1,1]
	s_waitcnt lgkmcnt(1)
	v_mov_b32_e32 v12, v28
	s_waitcnt lgkmcnt(0)
	v_mov_b32_e32 v13, v32
	v_pk_fma_f32 v[24:25], v[124:125], v[12:13], v[10:11] op_sel_hi:[0,1,1]
	ds_read_b128 v[10:13], v27 offset:16432
	ds_read_b128 v[36:39], v27 offset:20528
	v_mov_b32_e32 v32, v29
	s_waitcnt lgkmcnt(1)
	v_mov_b32_e32 v50, v10
	s_waitcnt lgkmcnt(0)
	v_mov_b32_e32 v51, v36
	v_pk_fma_f32 v[8:9], v[124:125], v[50:51], v[8:9] op_sel_hi:[0,1,1]
	ds_read_b128 v[50:53], v27 offset:24624
	ds_read_b128 v[62:65], v27 offset:28720
	v_mov_b32_e32 v36, v11
	v_mov_b32_e32 v10, v2
	v_mov_b32_e32 v11, v16
	s_waitcnt lgkmcnt(1)
	v_mov_b32_e32 v66, v50
	s_waitcnt lgkmcnt(0)
	v_mov_b32_e32 v67, v62
	v_pk_fma_f32 v[4:5], v[124:125], v[66:67], v[4:5] op_sel_hi:[0,1,1]
	ds_read_b128 v[66:69], v27 offset:32816
	v_mov_b32_e32 v62, v51
	v_mov_b32_e32 v16, v3
	v_add_u32_e32 v27, 64, v27
	s_waitcnt lgkmcnt(0)
	v_fmac_f32_e32 v26, v124, v66
	s_waitcnt vmcnt(2)
	v_pk_fma_f32 v[6:7], v[126:127], v[14:15], v[18:19] op_sel_hi:[0,1,1]
	v_pk_fma_f32 v[14:15], v[126:127], v[32:33], v[24:25] op_sel_hi:[0,1,1]
	v_pk_fma_f32 v[8:9], v[126:127], v[36:37], v[8:9] op_sel_hi:[0,1,1]
	v_pk_fma_f32 v[4:5], v[126:127], v[62:63], v[4:5] op_sel_hi:[0,1,1]
	v_fmac_f32_e32 v26, v126, v67
	s_waitcnt vmcnt(1)
	v_pk_fma_f32 v[6:7], v[128:129], v[10:11], v[6:7] op_sel_hi:[0,1,1]
	v_mov_b32_e32 v10, v30
	v_mov_b32_e32 v11, v34
	v_pk_fma_f32 v[10:11], v[128:129], v[10:11], v[14:15] op_sel_hi:[0,1,1]
	v_mov_b32_e32 v14, v12
	v_mov_b32_e32 v15, v38
	v_pk_fma_f32 v[8:9], v[128:129], v[14:15], v[8:9] op_sel_hi:[0,1,1]
	v_mov_b32_e32 v14, v52
	v_mov_b32_e32 v15, v64
	v_pk_fma_f32 v[4:5], v[128:129], v[14:15], v[4:5] op_sel_hi:[0,1,1]
	v_fmac_f32_e32 v26, v128, v68
	v_mov_b32_e32 v34, v31
	s_nop 0
	v_mov_b32_e32 v38, v13
	v_mov_b32_e32 v64, v53
	s_waitcnt vmcnt(0)
	v_pk_fma_f32 v[18:19], v[130:131], v[16:17], v[6:7] op_sel_hi:[0,1,1]
	v_pk_fma_f32 v[16:17], v[130:131], v[34:35], v[10:11] op_sel_hi:[0,1,1]
	v_pk_fma_f32 v[14:15], v[130:131], v[38:39], v[8:9] op_sel_hi:[0,1,1]
	v_pk_fma_f32 v[12:13], v[130:131], v[64:65], v[4:5] op_sel_hi:[0,1,1]
	v_fmac_f32_e32 v26, v130, v69
	s_cbranch_scc1 .LBB0_53

.LBB0_59:
	v_lshl_add_u64 v[52:53], v[50:51], 0, s[8:9]
	global_load_dword v100, v[52:53], off
	v_mov_b32_e32 v140, v52
	v_mov_b32_e32 v141, v53
	v_add_co_u32_e32 v140, vcc, 0x4000, v140
	s_nop 1
	v_addc_co_u32_e32 v141, vcc, 0, v141, vcc
	global_load_dword v102, v[140:141], off
	v_add_co_u32_e32 v140, vcc, 0x4000, v140
	s_nop 1
	v_addc_co_u32_e32 v141, vcc, 0, v141, vcc
	global_load_dword v104, v[140:141], off
	v_add_co_u32_e32 v140, vcc, 0x4000, v140
	s_nop 1
	v_addc_co_u32_e32 v141, vcc, 0, v141, vcc
	global_load_dword v106, v[140:141], off
	v_add_co_u32_e32 v140, vcc, 0x4000, v140
	s_nop 1
	v_addc_co_u32_e32 v141, vcc, 0, v141, vcc
	global_load_dword v108, v[140:141], off
	v_add_co_u32_e32 v140, vcc, 0x4000, v140
	s_nop 1
	v_addc_co_u32_e32 v141, vcc, 0, v141, vcc
	global_load_dword v110, v[140:141], off
	v_add_co_u32_e32 v140, vcc, 0x4000, v140
	s_nop 1
	v_addc_co_u32_e32 v141, vcc, 0, v141, vcc
	global_load_dword v112, v[140:141], off
	v_add_co_u32_e32 v140, vcc, 0x4000, v140
	s_nop 1
	v_addc_co_u32_e32 v141, vcc, 0, v141, vcc
	global_load_dword v114, v[140:141], off
	v_add_co_u32_e32 v140, vcc, 0x4000, v140
	s_nop 1
	v_addc_co_u32_e32 v141, vcc, 0, v141, vcc
	global_load_dword v116, v[140:141], off
	v_add_co_u32_e32 v140, vcc, 0x4000, v140
	s_nop 1
	v_addc_co_u32_e32 v141, vcc, 0, v141, vcc
	global_load_dword v118, v[140:141], off
	v_add_co_u32_e32 v140, vcc, 0x4000, v140
	s_nop 1
	v_addc_co_u32_e32 v141, vcc, 0, v141, vcc
	global_load_dword v120, v[140:141], off
	v_add_co_u32_e32 v140, vcc, 0x4000, v140
	s_nop 1
	v_addc_co_u32_e32 v141, vcc, 0, v141, vcc
	global_load_dword v122, v[140:141], off
	v_add_co_u32_e32 v140, vcc, 0x4000, v140
	s_nop 1
	v_addc_co_u32_e32 v141, vcc, 0, v141, vcc
	global_load_dword v124, v[140:141], off
	v_add_co_u32_e32 v140, vcc, 0x4000, v140
	s_nop 1
	v_addc_co_u32_e32 v141, vcc, 0, v141, vcc
	global_load_dword v126, v[140:141], off
	v_add_co_u32_e32 v140, vcc, 0x4000, v140
	s_nop 1
	v_addc_co_u32_e32 v141, vcc, 0, v141, vcc
	global_load_dword v128, v[140:141], off
	v_add_co_u32_e32 v140, vcc, 0x4000, v140
	s_nop 1
	v_addc_co_u32_e32 v141, vcc, 0, v141, vcc
	global_load_dword v130, v[140:141], off
	ds_read_b128 v[20:23], v62
	ds_read_b128 v[8:11], v62 offset:16
	ds_read_b128 v[4:7], v62 offset:32
	ds_read_b128 v[0:3], v62 offset:48
	ds_read_b128 v[24:27], v62 offset:4096
	s_waitcnt lgkmcnt(4)
	v_mov_b32_e32 v28, v20
	s_mov_b32 s1, 0x10000
	s_add_u32 s8, s8, 0x40000
	s_addc_u32 s9, s9, 0
	s_waitcnt lgkmcnt(0)
	v_mov_b32_e32 v29, v24
	v_mov_b32_e32 v24, v21
	s_cmp_lg_u32 s8, 0x100000
	s_waitcnt vmcnt(15)
	v_pk_fma_f32 v[78:79], v[100:101], v[28:29], v[16:17] op_sel_hi:[0,1,1]
	ds_read_b128 v[28:31], v62 offset:8192
	ds_read_b128 v[32:35], v62 offset:12288
	s_waitcnt lgkmcnt(1)
	v_mov_b32_e32 v16, v28
	s_waitcnt lgkmcnt(0)
	v_mov_b32_e32 v17, v32
	v_pk_fma_f32 v[80:81], v[100:101], v[16:17], v[18:19] op_sel_hi:[0,1,1]
	ds_read_b128 v[16:19], v62 offset:16384
	ds_read_b128 v[36:39], v62 offset:20480
	v_mov_b32_e32 v32, v29
	v_mov_b32_e32 v28, v22
	v_mov_b32_e32 v29, v26
	s_waitcnt lgkmcnt(1)
	v_mov_b32_e32 v64, v16
	s_waitcnt lgkmcnt(0)
	v_mov_b32_e32 v65, v36
	v_pk_fma_f32 v[14:15], v[100:101], v[64:65], v[14:15] op_sel_hi:[0,1,1]
	ds_read_b128 v[64:67], v62 offset:24576
	ds_read_b128 v[68:71], v62 offset:28672
	v_mov_b32_e32 v36, v17
	v_mov_b32_e32 v26, v23
	s_waitcnt lgkmcnt(1)
	v_mov_b32_e32 v72, v64
	s_waitcnt lgkmcnt(0)
	v_mov_b32_e32 v73, v68
	v_pk_fma_f32 v[12:13], v[100:101], v[72:73], v[12:13] op_sel_hi:[0,1,1]
	ds_read_b128 v[72:75], v62 offset:32768
	v_mov_b32_e32 v68, v65
	s_waitcnt lgkmcnt(0)
	v_fmac_f32_e32 v61, v100, v72
	s_waitcnt vmcnt(14)
	v_pk_fma_f32 v[20:21], v[102:103], v[24:25], v[78:79] op_sel_hi:[0,1,1]
	v_pk_fma_f32 v[24:25], v[102:103], v[32:33], v[80:81] op_sel_hi:[0,1,1]
	v_pk_fma_f32 v[14:15], v[102:103], v[36:37], v[14:15] op_sel_hi:[0,1,1]
	v_pk_fma_f32 v[12:13], v[102:103], v[68:69], v[12:13] op_sel_hi:[0,1,1]
	v_fmac_f32_e32 v61, v102, v73
	s_waitcnt vmcnt(13)
	v_pk_fma_f32 v[20:21], v[104:105], v[28:29], v[20:21] op_sel_hi:[0,1,1]
	v_mov_b32_e32 v28, v30
	v_mov_b32_e32 v29, v34
	v_pk_fma_f32 v[24:25], v[104:105], v[28:29], v[24:25] op_sel_hi:[0,1,1]
	v_mov_b32_e32 v28, v18
	v_mov_b32_e32 v29, v38
	v_pk_fma_f32 v[14:15], v[104:105], v[28:29], v[14:15] op_sel_hi:[0,1,1]
	v_mov_b32_e32 v28, v66
	v_mov_b32_e32 v29, v70
	v_pk_fma_f32 v[12:13], v[104:105], v[28:29], v[12:13] op_sel_hi:[0,1,1]
	v_fmac_f32_e32 v61, v104, v74
	v_mov_b32_e32 v34, v31
	s_nop 0
	v_mov_b32_e32 v38, v19
	v_mov_b32_e32 v70, v67
	s_waitcnt vmcnt(12)
	v_pk_fma_f32 v[20:21], v[106:107], v[26:27], v[20:21] op_sel_hi:[0,1,1]
	v_pk_fma_f32 v[16:17], v[106:107], v[34:35], v[24:25] op_sel_hi:[0,1,1]
	v_pk_fma_f32 v[14:15], v[106:107], v[38:39], v[14:15] op_sel_hi:[0,1,1]
	v_pk_fma_f32 v[12:13], v[106:107], v[70:71], v[12:13] op_sel_hi:[0,1,1]
	v_fmac_f32_e32 v61, v106, v75
	ds_read_b128 v[22:25], v62 offset:4112
	s_nop 0
	v_mov_b32_e32 v26, v8
	s_waitcnt lgkmcnt(0)
	v_mov_b32_e32 v27, v22
	v_mov_b32_e32 v22, v9
	s_mov_b32 s1, 0x20000
	s_waitcnt vmcnt(11)
	v_pk_fma_f32 v[20:21], v[108:109], v[26:27], v[20:21] op_sel_hi:[0,1,1]
	ds_read_b128 v[26:29], v62 offset:8208
	ds_read_b128 v[30:33], v62 offset:12304
	s_waitcnt lgkmcnt(1)
	v_mov_b32_e32 v34, v26
	s_waitcnt lgkmcnt(0)
	v_mov_b32_e32 v35, v30
	v_pk_fma_f32 v[38:39], v[108:109], v[34:35], v[16:17] op_sel_hi:[0,1,1]
	ds_read_b128 v[34:37], v62 offset:16400
	ds_read_b128 v[64:67], v62 offset:20496
	v_mov_b32_e32 v30, v27
	s_waitcnt lgkmcnt(1)
	v_mov_b32_e32 v16, v34
	s_waitcnt lgkmcnt(0)
	v_mov_b32_e32 v17, v64
	v_pk_fma_f32 v[76:77], v[108:109], v[16:17], v[14:15] op_sel_hi:[0,1,1]
	ds_read_b128 v[14:17], v62 offset:24592
	ds_read_b128 v[68:71], v62 offset:28688
	v_mov_b32_e32 v64, v35
	s_waitcnt lgkmcnt(1)
	v_mov_b32_e32 v72, v14
	s_waitcnt lgkmcnt(0)
	v_mov_b32_e32 v73, v68
	v_pk_fma_f32 v[12:13], v[108:109], v[72:73], v[12:13] op_sel_hi:[0,1,1]
	ds_read_b128 v[72:75], v62 offset:32784
	v_mov_b32_e32 v68, v15
	v_mov_b32_e32 v14, v10
	v_mov_b32_e32 v15, v24
	v_mov_b32_e32 v24, v11
	s_waitcnt lgkmcnt(0)
	v_fmac_f32_e32 v61, v108, v72
	s_waitcnt vmcnt(10)
	v_pk_fma_f32 v[18:19], v[110:111], v[22:23], v[20:21] op_sel_hi:[0,1,1]
	v_pk_fma_f32 v[20:21], v[110:111], v[30:31], v[38:39] op_sel_hi:[0,1,1]
	v_pk_fma_f32 v[22:23], v[110:111], v[64:65], v[76:77] op_sel_hi:[0,1,1]
	v_pk_fma_f32 v[12:13], v[110:111], v[68:69], v[12:13] op_sel_hi:[0,1,1]
	v_fmac_f32_e32 v61, v110, v73
	s_waitcnt vmcnt(9)
	v_pk_fma_f32 v[14:15], v[112:113], v[14:15], v[18:19] op_sel_hi:[0,1,1]
	v_mov_b32_e32 v18, v28
	v_mov_b32_e32 v19, v32
	v_pk_fma_f32 v[18:19], v[112:113], v[18:19], v[20:21] op_sel_hi:[0,1,1]
	v_mov_b32_e32 v20, v36
	v_mov_b32_e32 v21, v66
	v_pk_fma_f32 v[20:21], v[112:113], v[20:21], v[22:23] op_sel_hi:[0,1,1]
	v_mov_b32_e32 v22, v16
	v_mov_b32_e32 v23, v70
	v_pk_fma_f32 v[12:13], v[112:113], v[22:23], v[12:13] op_sel_hi:[0,1,1]
	v_fmac_f32_e32 v61, v112, v74
	v_mov_b32_e32 v32, v29
	s_nop 0
	v_mov_b32_e32 v66, v37
	v_mov_b32_e32 v70, v17
	s_waitcnt vmcnt(8)
	v_pk_fma_f32 v[14:15], v[114:115], v[24:25], v[14:15] op_sel_hi:[0,1,1]
	v_pk_fma_f32 v[22:23], v[114:115], v[32:33], v[18:19] op_sel_hi:[0,1,1]
	v_pk_fma_f32 v[28:29], v[114:115], v[66:67], v[20:21] op_sel_hi:[0,1,1]
	v_pk_fma_f32 v[36:37], v[114:115], v[70:71], v[12:13] op_sel_hi:[0,1,1]
	v_fmac_f32_e32 v61, v114, v75
	v_mov_b32_e32 v12, v4
	s_nop 0
	ds_read_b128 v[8:11], v62 offset:4128
	s_mov_b32 s1, 0x28000
	s_waitcnt lgkmcnt(0)
	v_mov_b32_e32 v13, v8
	v_mov_b32_e32 v8, v5
	s_waitcnt vmcnt(7)
	v_pk_fma_f32 v[66:67], v[116:117], v[12:13], v[14:15] op_sel_hi:[0,1,1]
	ds_read_b128 v[12:15], v62 offset:8224
	ds_read_b128 v[16:19], v62 offset:12320
	s_waitcnt lgkmcnt(1)
	v_mov_b32_e32 v20, v12
	s_waitcnt lgkmcnt(0)
	v_mov_b32_e32 v21, v16
	v_pk_fma_f32 v[68:69], v[116:117], v[20:21], v[22:23] op_sel_hi:[0,1,1]
	ds_read_b128 v[20:23], v62 offset:16416
	ds_read_b128 v[24:27], v62 offset:20512
	v_mov_b32_e32 v16, v13
	s_waitcnt lgkmcnt(1)
	v_mov_b32_e32 v30, v20
	s_waitcnt lgkmcnt(0)
	v_mov_b32_e32 v31, v24
	v_pk_fma_f32 v[70:71], v[116:117], v[30:31], v[28:29] op_sel_hi:[0,1,1]
	ds_read_b128 v[28:31], v62 offset:24608
	ds_read_b128 v[32:35], v62 offset:28704
	v_mov_b32_e32 v24, v21
	s_waitcnt lgkmcnt(1)
	v_mov_b32_e32 v38, v28
	s_waitcnt lgkmcnt(0)
	v_mov_b32_e32 v39, v32
	v_pk_fma_f32 v[72:73], v[116:117], v[38:39], v[36:37] op_sel_hi:[0,1,1]
	ds_read_b128 v[36:39], v62 offset:32800
	v_mov_b32_e32 v32, v29
	s_waitcnt lgkmcnt(0)
	v_fmac_f32_e32 v61, v116, v36
	s_waitcnt vmcnt(6)
	v_pk_fma_f32 v[8:9], v[118:119], v[8:9], v[66:67] op_sel_hi:[0,1,1]
	v_pk_fma_f32 v[12:13], v[118:119], v[16:17], v[68:69] op_sel_hi:[0,1,1]
	v_pk_fma_f32 v[16:17], v[118:119], v[24:25], v[70:71] op_sel_hi:[0,1,1]
	v_pk_fma_f32 v[20:21], v[118:119], v[32:33], v[72:73] op_sel_hi:[0,1,1]
	v_fmac_f32_e32 v61, v118, v37
	v_mov_b32_e32 v24, v6
	s_nop 0
	v_mov_b32_e32 v25, v10
	s_mov_b32 s1, 0x2c000
	v_mov_b32_e32 v10, v7
	s_waitcnt vmcnt(5)
	v_pk_fma_f32 v[8:9], v[120:121], v[24:25], v[8:9] op_sel_hi:[0,1,1]
	v_mov_b32_e32 v24, v14
	v_mov_b32_e32 v25, v18
	v_pk_fma_f32 v[12:13], v[120:121], v[24:25], v[12:13] op_sel_hi:[0,1,1]
	v_mov_b32_e32 v24, v22
	v_mov_b32_e32 v25, v26
	v_pk_fma_f32 v[16:17], v[120:121], v[24:25], v[16:17] op_sel_hi:[0,1,1]
	v_mov_b32_e32 v24, v30
	v_mov_b32_e32 v25, v34
	v_pk_fma_f32 v[20:21], v[120:121], v[24:25], v[20:21] op_sel_hi:[0,1,1]
	v_fmac_f32_e32 v61, v120, v38
	v_mov_b32_e32 v18, v15
	s_nop 0
	v_mov_b32_e32 v26, v23
	v_mov_b32_e32 v34, v31
	s_mov_b32 s1, 0x34000
	s_waitcnt vmcnt(4)
	v_pk_fma_f32 v[24:25], v[122:123], v[10:11], v[8:9] op_sel_hi:[0,1,1]
	v_pk_fma_f32 v[10:11], v[122:123], v[18:19], v[12:13] op_sel_hi:[0,1,1]
	v_pk_fma_f32 v[8:9], v[122:123], v[26:27], v[16:17] op_sel_hi:[0,1,1]
	v_pk_fma_f32 v[6:7], v[122:123], v[34:35], v[20:21] op_sel_hi:[0,1,1]
	v_fmac_f32_e32 v61, v122, v39
	ds_read_b128 v[12:15], v62 offset:4144
	s_nop 0
	v_mov_b32_e32 v16, v0
	s_waitcnt lgkmcnt(0)
	v_mov_b32_e32 v17, v12
	v_mov_b32_e32 v12, v1
	s_waitcnt vmcnt(3)
	v_pk_fma_f32 v[64:65], v[124:125], v[16:17], v[24:25] op_sel_hi:[0,1,1]
	ds_read_b128 v[16:19], v62 offset:8240
	ds_read_b128 v[20:23], v62 offset:12336
	s_waitcnt lgkmcnt(1)
	v_mov_b32_e32 v24, v16
	s_waitcnt lgkmcnt(0)
	v_mov_b32_e32 v25, v20
	v_pk_fma_f32 v[66:67], v[124:125], v[24:25], v[10:11] op_sel_hi:[0,1,1]
	ds_read_b128 v[24:27], v62 offset:16432
	ds_read_b128 v[28:31], v62 offset:20528
	v_mov_b32_e32 v20, v17
	s_waitcnt lgkmcnt(1)
	v_mov_b32_e32 v10, v24
	s_waitcnt lgkmcnt(0)
	v_mov_b32_e32 v11, v28
	v_pk_fma_f32 v[68:69], v[124:125], v[10:11], v[8:9] op_sel_hi:[0,1,1]
	ds_read_b128 v[8:11], v62 offset:24624
	ds_read_b128 v[32:35], v62 offset:28720
	v_mov_b32_e32 v28, v25
	s_waitcnt lgkmcnt(1)
	v_mov_b32_e32 v36, v8
	s_waitcnt lgkmcnt(0)
	v_mov_b32_e32 v37, v32
	v_pk_fma_f32 v[6:7], v[124:125], v[36:37], v[6:7] op_sel_hi:[0,1,1]
	ds_read_b128 v[36:39], v62 offset:32816
	v_mov_b32_e32 v32, v9
	v_mov_b32_e32 v8, v2
	v_mov_b32_e32 v9, v14
	v_mov_b32_e32 v14, v3
	s_waitcnt lgkmcnt(0)
	v_fmac_f32_e32 v61, v124, v36
	s_mov_b32 s1, 0x38000
	s_nop 0
	v_add_u32_e32 v62, 64, v62
	s_waitcnt vmcnt(2)
	v_pk_fma_f32 v[4:5], v[126:127], v[12:13], v[64:65] op_sel_hi:[0,1,1]
	v_pk_fma_f32 v[12:13], v[126:127], v[20:21], v[66:67] op_sel_hi:[0,1,1]
	v_pk_fma_f32 v[16:17], v[126:127], v[28:29], v[68:69] op_sel_hi:[0,1,1]
	v_pk_fma_f32 v[6:7], v[126:127], v[32:33], v[6:7] op_sel_hi:[0,1,1]
	v_fmac_f32_e32 v61, v126, v37
	s_waitcnt vmcnt(1)
	v_pk_fma_f32 v[4:5], v[128:129], v[8:9], v[4:5] op_sel_hi:[0,1,1]
	v_mov_b32_e32 v8, v18
	v_mov_b32_e32 v9, v22
	v_pk_fma_f32 v[8:9], v[128:129], v[8:9], v[12:13] op_sel_hi:[0,1,1]
	v_mov_b32_e32 v12, v26
	v_mov_b32_e32 v13, v30
	v_pk_fma_f32 v[12:13], v[128:129], v[12:13], v[16:17] op_sel_hi:[0,1,1]
	v_mov_b32_e32 v16, v10
	v_mov_b32_e32 v17, v34
	v_pk_fma_f32 v[6:7], v[128:129], v[16:17], v[6:7] op_sel_hi:[0,1,1]
	v_fmac_f32_e32 v61, v128, v38
	v_mov_b32_e32 v22, v19
	s_nop 0
	v_mov_b32_e32 v30, v27
	v_mov_b32_e32 v34, v11
	s_waitcnt vmcnt(0)
	v_pk_fma_f32 v[16:17], v[130:131], v[14:15], v[4:5] op_sel_hi:[0,1,1]
	v_pk_fma_f32 v[18:19], v[130:131], v[22:23], v[8:9] op_sel_hi:[0,1,1]
	v_pk_fma_f32 v[14:15], v[130:131], v[30:31], v[12:13] op_sel_hi:[0,1,1]
	v_pk_fma_f32 v[12:13], v[130:131], v[34:35], v[6:7] op_sel_hi:[0,1,1]
	v_fmac_f32_e32 v61, v130, v39
	s_cbranch_scc1 .LBB0_59
	v_add_u32_e32 v0, v54, v55
	s_mov_b32 s52, 0x8000
	v_add_u32_e32 v1, 0x9000, v0
	ds_write2_b32 v1, v16, v17 offset1:32
	ds_write2_b32 v1, v18, v19 offset0:64 offset1:96
	ds_write2_b32 v1, v14, v15 offset0:128 offset1:160
	ds_write2_b32 v1, v12, v13 offset0:192 offset1:224
	ds_write_b32 v0, v61 offset:37888
	s_waitcnt lgkmcnt(0)
	s_barrier
	s_and_saveexec_b64 s[8:9], s[40:41]
	s_cbranch_execz .LBB0_38
	v_add_u32_e32 v0, v54, v56
	ds_read_b32 v1, v0 offset:36864
	ds_read_b32 v2, v0 offset:38016
	ds_read_b32 v3, v0 offset:39168
	ds_read_b32 v4, v0 offset:40320
	ds_read_b32 v5, v0 offset:41472
	ds_read_b32 v6, v0 offset:42624
	ds_read_b32 v7, v0 offset:43776
	ds_read_b32 v8, v0 offset:44928
	s_waitcnt lgkmcnt(7)
	v_add_f32_e32 v1, 0, v1
	s_waitcnt lgkmcnt(6)
	v_add_f32_e32 v1, v1, v2
	s_waitcnt lgkmcnt(5)
	v_add_f32_e32 v1, v1, v3
	s_waitcnt lgkmcnt(4)
	v_add_f32_e32 v1, v1, v4
	s_waitcnt lgkmcnt(3)
	v_add_f32_e32 v1, v1, v5
	s_waitcnt lgkmcnt(2)
	v_add_f32_e32 v1, v1, v6
	s_waitcnt lgkmcnt(1)
	v_add_f32_e32 v1, v1, v7
	s_waitcnt lgkmcnt(0)
	v_add_f32_e32 v1, v1, v8
	ds_read_b32 v2, v0 offset:46080
	ds_read_b32 v3, v0 offset:47232
	ds_read_b32 v4, v0 offset:48384
	ds_read_b32 v5, v0 offset:49536
	ds_read_b32 v6, v0 offset:50688
	ds_read_b32 v7, v0 offset:51840
	ds_read_b32 v8, v0 offset:52992
	ds_read_b32 v0, v0 offset:54144
	s_waitcnt lgkmcnt(7)
	v_add_f32_e32 v1, v1, v2
	s_waitcnt lgkmcnt(6)
	v_add_f32_e32 v1, v1, v3
	s_waitcnt lgkmcnt(5)
	v_add_f32_e32 v1, v1, v4
	s_waitcnt lgkmcnt(4)
	v_add_f32_e32 v1, v1, v5
	s_waitcnt lgkmcnt(3)
	v_add_f32_e32 v1, v1, v6
	s_waitcnt lgkmcnt(2)
	v_add_f32_e32 v1, v1, v7
	s_waitcnt lgkmcnt(1)
	v_add_f32_e32 v1, v1, v8
	s_waitcnt lgkmcnt(0)
	v_add_f32_e32 v2, v1, v0
	v_mov_b32_e32 v0, 0x24000
	v_mad_i64_i32 v[0:1], s[0:1], s0, v0, v[44:45]
	v_lshl_add_u64 v[0:1], s[68:69], 2, v[0:1]
	v_lshlrev_b32_e32 v98, 2, v40
	v_lshl_add_u64 v[0:1], v[0:1], 0, v[98:99]
	global_store_dword v[0:1], v2, off
	s_branch .LBB0_38

.Lmla_norescale:
	s_add_i32 s10, s1, -1
	s_and_b32 s11, s10, 1
	s_mul_i32 s7, s11, 0x3400
	v_add_u32_e32 v147, s7, v149
	ds_read_b128 v[110:113], v147
	ds_read_b128 v[114:117], v147 offset:32
	ds_read_b128 v[118:121], v147 offset:64
	ds_read_b128 v[152:155], v147 offset:96
	s_and_b32 s6, s1, 1
	v_exp_f32_e32 v141, v48
	v_exp_f32_e32 v157, v49
	v_exp_f32_e32 v158, v50
	v_exp_f32_e32 v159, v51
	v_exp_f32_e32 v160, v52
	v_exp_f32_e32 v161, v53
	v_exp_f32_e32 v162, v54
	v_exp_f32_e32 v163, v55
	v_exp_f32_e32 v164, v56
	v_exp_f32_e32 v165, v57
	v_exp_f32_e32 v166, v58
	v_exp_f32_e32 v167, v59
	v_exp_f32_e32 v168, v60
	v_exp_f32_e32 v169, v61
	v_exp_f32_e32 v170, v62
	v_exp_f32_e32 v171, v63
	s_waitcnt lgkmcnt(3)
	v_mfma_f32_32x32x16_bf16 v[48:63], v[110:113], v[106:109], v[64:79]
	ds_read_b128 v[234:237], v147 offset:128
	v_exp_f32_e32 v172, v32
	v_exp_f32_e32 v173, v33
	v_exp_f32_e32 v174, v34
	s_waitcnt lgkmcnt(3)
	v_mfma_f32_32x32x16_bf16 v[48:63], v[114:117], v[102:105], v[48:63]
	ds_read_b128 v[212:215], v147 offset:160
	v_exp_f32_e32 v175, v35
	v_exp_f32_e32 v176, v36
	v_exp_f32_e32 v177, v37
	s_waitcnt lgkmcnt(3)
	v_mfma_f32_32x32x16_bf16 v[48:63], v[118:121], v[92:95], v[48:63]
	ds_read_b128 v[216:219], v147 offset:6656
	v_exp_f32_e32 v178, v38
	v_exp_f32_e32 v179, v39
	v_exp_f32_e32 v187, v40
	s_waitcnt lgkmcnt(3)
	v_mfma_f32_32x32x16_bf16 v[48:63], v[152:155], v[88:91], v[48:63]
	ds_read_b128 v[238:241], v147 offset:6688
	v_exp_f32_e32 v188, v41
	v_exp_f32_e32 v189, v42
	v_exp_f32_e32 v190, v43
	s_waitcnt lgkmcnt(3)
	v_mfma_f32_32x32x16_bf16 v[48:63], v[234:237], v[84:87], v[48:63]
	ds_read_b128 v[242:245], v147 offset:6720
	v_exp_f32_e32 v191, v44
	v_exp_f32_e32 v192, v45
	v_exp_f32_e32 v193, v46
	s_waitcnt lgkmcnt(3)
	v_mfma_f32_32x32x16_bf16 v[48:63], v[212:215], v[80:83], v[48:63]
	ds_read_b128 v[246:249], v147 offset:6752
	v_exp_f32_e32 v194, v47
	v_cvt_pk_bf16_f32 v196, v141, v157
	v_cvt_pk_bf16_f32 v197, v158, v159
	s_waitcnt lgkmcnt(3)
	v_mfma_f32_32x32x16_bf16 v[32:47], v[216:219], v[106:109], v[64:79]
	ds_read_b128 v[110:113], v147 offset:6784
	v_cvt_pk_bf16_f32 v198, v160, v161
	v_cvt_pk_bf16_f32 v199, v162, v163
	v_cvt_pk_bf16_f32 v200, v164, v165
	v_cvt_pk_bf16_f32 v201, v166, v167
	s_waitcnt lgkmcnt(3)
	v_mfma_f32_32x32x16_bf16 v[32:47], v[238:241], v[102:105], v[32:47]
	ds_read_b128 v[114:117], v147 offset:6816
	v_cvt_pk_bf16_f32 v202, v168, v169
	v_cvt_pk_bf16_f32 v203, v170, v171
	v_cvt_pk_bf16_f32 v204, v172, v173
	v_cvt_pk_bf16_f32 v205, v174, v175
	s_waitcnt lgkmcnt(3)
	v_mfma_f32_32x32x16_bf16 v[32:47], v[242:245], v[92:95], v[32:47]
	s_mul_i32 s7, s6, 0x2400
	v_add_u32_e32 v156, s7, v97
	ds_read_b64_tr_b16 v[118:119], v156 offset:26624
	ds_read_b64_tr_b16 v[120:121], v156 offset:27776
	ds_read_b64_tr_b16 v[154:155], v156 offset:27840
	ds_read_b64_tr_b16 v[152:153], v156 offset:26688
	v_cvt_pk_bf16_f32 v206, v176, v177
	v_cvt_pk_bf16_f32 v207, v178, v179
	v_cvt_pk_bf16_f32 v208, v187, v188
	s_waitcnt lgkmcnt(6)
	v_mfma_f32_32x32x16_bf16 v[32:47], v[246:249], v[88:91], v[32:47]
	ds_read_b64_tr_b16 v[234:235], v156 offset:28928
	ds_read_b64_tr_b16 v[236:237], v156 offset:30080
	ds_read_b64_tr_b16 v[214:215], v156 offset:30144
	ds_read_b64_tr_b16 v[212:213], v156 offset:28992
	v_cvt_pk_bf16_f32 v209, v189, v190
	v_cvt_pk_bf16_f32 v210, v191, v192
	v_cvt_pk_bf16_f32 v211, v193, v194
	v_add_f32_e32 v195, v172, v141
	s_waitcnt lgkmcnt(9)
	v_mfma_f32_32x32x16_bf16 v[32:47], v[110:113], v[84:87], v[32:47]
	ds_read_b64_tr_b16 v[216:217], v156 offset:31232
	ds_read_b64_tr_b16 v[218:219], v156 offset:32384
	ds_read_b64_tr_b16 v[240:241], v156 offset:32448
	ds_read_b64_tr_b16 v[238:239], v156 offset:31296
	v_add_f32_e32 v195, 0, v195
	v_add_f32_e32 v101, v173, v157
	v_add_f32_e32 v195, v101, v195
	v_add_f32_e32 v101, v174, v158
	s_waitcnt lgkmcnt(12)
	v_mfma_f32_32x32x16_bf16 v[32:47], v[114:117], v[80:83], v[32:47]
	ds_read_b64_tr_b16 v[242:243], v156 offset:33536
	ds_read_b64_tr_b16 v[244:245], v156 offset:34688
	ds_read_b64_tr_b16 v[248:249], v156 offset:34752
	ds_read_b64_tr_b16 v[246:247], v156 offset:33600
	v_add_f32_e32 v195, v101, v195
	v_add_f32_e32 v101, v175, v159
	v_add_f32_e32 v195, v101, v195
	s_nop 1
	v_add_f32_e32 v101, v176, v160
	v_add_f32_e32 v195, v101, v195
	v_add_f32_e32 v101, v177, v161
	v_add_f32_e32 v195, v101, v195
	s_waitcnt lgkmcnt(14)
	v_mfma_f32_32x32x16_bf16 v[16:31], v[118:121], v[196:199], v[16:31]
	v_add_f32_e32 v101, v178, v162
	v_add_f32_e32 v195, v101, v195
	v_add_f32_e32 v101, v179, v163
	v_max3_f32 v100, v48, v49, v50
	v_max3_f32 v100, v100, v51, v52
	v_max3_f32 v100, v100, v53, v54
	s_waitcnt lgkmcnt(12)
	v_mfma_f32_32x32x16_bf16 v[0:15], v[152:155], v[196:199], v[0:15]
	s_mulk_i32 s6, 0x3400
	s_add_i32 s12, s6, 0
	v_add3_u32 v156, s12, v150, v134
	s_waitcnt vmcnt(1)
	ds_write_b128 v156, v[130:133]
	s_and_saveexec_b64 s[6:7], s[38:39]
	v_add3_u32 v156, s12, v151, v136
	ds_write_b128 v156, v[122:125] offset:128
	s_or_b64 exec, exec, s[6:7]
	v_add_f32_e32 v195, v101, v195
	v_add_f32_e32 v101, v187, v164
	v_max3_f32 v100, v100, v55, v56
	v_max3_f32 v100, v100, v57, v58
	s_waitcnt lgkmcnt(11)
	v_mfma_f32_32x32x16_bf16 v[16:31], v[234:237], v[200:203], v[16:31]
	v_add_f32_e32 v195, v101, v195
	v_add_f32_e32 v101, v188, v165
	v_add_f32_e32 v195, v101, v195
	v_max3_f32 v100, v100, v59, v60
	v_max3_f32 v100, v100, v61, v62
	v_max3_f32 v100, v100, v63, v63
	s_waitcnt lgkmcnt(9)
	v_mfma_f32_32x32x16_bf16 v[0:15], v[212:215], v[200:203], v[0:15]
	s_mulk_i32 s11, 0x2400
	v_add_u32_e32 v156, s11, v135
	v_add_u32_e32 v228, 64, v140
	s_waitcnt vmcnt(0)
	ds_write_b128 v156, v[126:129] offset:26624
	s_waitcnt lgkmcnt(8)
	v_mfma_f32_32x32x16_bf16 v[16:31], v[216:219], v[204:207], v[16:31]
	v_add_f32_e32 v101, v189, v166
	v_add_f32_e32 v195, v101, v195
	v_add_f32_e32 v101, v190, v167
	v_add_f32_e32 v195, v101, v195
	v_max3_f32 v98, v32, v33, v34
	v_max3_f32 v98, v98, v35, v36
	v_max3_f32 v98, v98, v37, v38
	s_waitcnt lgkmcnt(6)
	v_mfma_f32_32x32x16_bf16 v[0:15], v[238:241], v[204:207], v[0:15]
	s_cmpk_lt_u32 s10, 0x42
	s_cbranch_scc0 .Lmla_noload
	v_ashrrev_i32_e32 v229, 31, v228
	v_lshlrev_b64 v[220:221], 10, v[228:229]
	v_lshl_add_u64 v[220:221], v[142:143], 0, v[220:221]
	global_load_dwordx4 v[130:133], v[220:221], off
	s_and_saveexec_b64 s[6:7], s[38:39]
	s_cbranch_execz .Lmla_norr
	v_ashrrev_i32_e32 v147, 31, v146
	v_lshlrev_b64 v[220:221], 6, v[146:147]
	v_lshl_add_u64 v[220:221], v[144:145], 0, v[220:221]
	global_load_dwordx4 v[122:125], v[220:221], off

.Lmla_noload:
	v_ashrrev_i32_e32 v141, 31, v140
	v_lshlrev_b64 v[220:221], 10, v[140:141]
	v_lshl_add_u64 v[220:221], v[142:143], 0, v[220:221]
	global_load_dwordx4 v[126:129], v[220:221], off offset:128
	s_waitcnt lgkmcnt(4)
	v_mfma_f32_32x32x16_bf16 v[16:31], v[242:245], v[208:211], v[16:31]
	v_add_f32_e32 v101, v191, v168
	v_add_f32_e32 v195, v101, v195
	v_add_f32_e32 v101, v192, v169
	v_add_f32_e32 v195, v101, v195
	v_add_f32_e32 v101, v193, v170
	v_max3_f32 v98, v98, v39, v40
	v_max3_f32 v98, v98, v41, v42
	v_max3_f32 v98, v98, v43, v44
	s_waitcnt lgkmcnt(2)
	v_mfma_f32_32x32x16_bf16 v[0:15], v[246:249], v[208:211], v[0:15]
	v_max3_f32 v98, v98, v45, v46
	v_max3_f32 v98, v98, v47, v47
	v_max3_f32 v100, v100, v98, v98
	ds_bpermute_b32 v98, v137, v100
	v_add_f32_e32 v195, v101, v195
	v_add_f32_e32 v101, v194, v171
	v_add_f32_e32 v195, v101, v195
	v_add_f32_e32 v138, v138, v195
	s_waitcnt lgkmcnt(0)
	v_max3_f32 v100, v100, v98, v100
	s_barrier
	s_add_i32 s1, s1, 1
	v_add_u32_e32 v146, 64, v146
	s_cmpk_eq_i32 s1, 0x44
	s_cbranch_scc1 .LBB0_559
	v_mov_b32_e32 v140, v228
	s_branch .LBB0_546

.LBB0_1228:
	v_lshl_add_u64 v[50:51], v[48:49], 0, s[6:7]
	global_load_dword v100, v[50:51], off
	v_mov_b32_e32 v140, v50
	v_mov_b32_e32 v141, v51
	v_add_co_u32_e32 v140, vcc, 0x6000, v140
	s_nop 1
	v_addc_co_u32_e32 v141, vcc, 0, v141, vcc
	global_load_dword v102, v[140:141], off
	v_add_co_u32_e32 v140, vcc, 0x6000, v140
	s_nop 1
	v_addc_co_u32_e32 v141, vcc, 0, v141, vcc
	global_load_dword v104, v[140:141], off
	v_add_co_u32_e32 v140, vcc, 0x6000, v140
	s_nop 1
	v_addc_co_u32_e32 v141, vcc, 0, v141, vcc
	global_load_dword v106, v[140:141], off
	v_add_co_u32_e32 v140, vcc, 0x6000, v140
	s_nop 1
	v_addc_co_u32_e32 v141, vcc, 0, v141, vcc
	global_load_dword v108, v[140:141], off
	v_add_co_u32_e32 v140, vcc, 0x6000, v140
	s_nop 1
	v_addc_co_u32_e32 v141, vcc, 0, v141, vcc
	global_load_dword v110, v[140:141], off
	v_add_co_u32_e32 v140, vcc, 0x6000, v140
	s_nop 1
	v_addc_co_u32_e32 v141, vcc, 0, v141, vcc
	global_load_dword v112, v[140:141], off
	v_add_co_u32_e32 v140, vcc, 0x6000, v140
	s_nop 1
	v_addc_co_u32_e32 v141, vcc, 0, v141, vcc
	global_load_dword v114, v[140:141], off
	v_add_co_u32_e32 v140, vcc, 0x6000, v140
	s_nop 1
	v_addc_co_u32_e32 v141, vcc, 0, v141, vcc
	global_load_dword v116, v[140:141], off
	v_add_co_u32_e32 v140, vcc, 0x6000, v140
	s_nop 1
	v_addc_co_u32_e32 v141, vcc, 0, v141, vcc
	global_load_dword v118, v[140:141], off
	v_add_co_u32_e32 v140, vcc, 0x6000, v140
	s_nop 1
	v_addc_co_u32_e32 v141, vcc, 0, v141, vcc
	global_load_dword v120, v[140:141], off
	v_add_co_u32_e32 v140, vcc, 0x6000, v140
	s_nop 1
	v_addc_co_u32_e32 v141, vcc, 0, v141, vcc
	global_load_dword v122, v[140:141], off
	v_add_co_u32_e32 v140, vcc, 0x6000, v140
	s_nop 1
	v_addc_co_u32_e32 v141, vcc, 0, v141, vcc
	global_load_dword v124, v[140:141], off
	v_add_co_u32_e32 v140, vcc, 0x6000, v140
	s_nop 1
	v_addc_co_u32_e32 v141, vcc, 0, v141, vcc
	global_load_dword v126, v[140:141], off
	v_add_co_u32_e32 v140, vcc, 0x6000, v140
	s_nop 1
	v_addc_co_u32_e32 v141, vcc, 0, v141, vcc
	global_load_dword v128, v[140:141], off
	v_add_co_u32_e32 v140, vcc, 0x6000, v140
	s_nop 1
	v_addc_co_u32_e32 v141, vcc, 0, v141, vcc
	global_load_dword v130, v[140:141], off
	ds_read_b128 v[20:23], v62
	ds_read_b128 v[8:11], v62 offset:16
	ds_read_b128 v[4:7], v62 offset:32
	ds_read_b128 v[0:3], v62 offset:48
	ds_read_b128 v[24:27], v62 offset:4096
	s_waitcnt lgkmcnt(4)
	v_mov_b32_e32 v28, v20
	s_mov_b32 s1, 0x12000
	s_add_u32 s6, s6, 0x60000
	s_addc_u32 s7, s7, 0
	s_waitcnt lgkmcnt(0)
	v_mov_b32_e32 v29, v24
	v_mov_b32_e32 v24, v21
	s_cmp_lg_u32 s6, 0x180000
	s_waitcnt vmcnt(15)
	v_pk_fma_f32 v[16:17], v[100:101], v[28:29], v[16:17] op_sel_hi:[0,1,1]
	ds_read_b128 v[28:31], v62 offset:8192
	ds_read_b128 v[32:35], v62 offset:12288
	s_waitcnt lgkmcnt(1)
	v_mov_b32_e32 v36, v28
	s_waitcnt lgkmcnt(0)
	v_mov_b32_e32 v37, v32
	v_pk_fma_f32 v[18:19], v[100:101], v[36:37], v[18:19] op_sel_hi:[0,1,1]
	ds_read_b128 v[36:39], v62 offset:16384
	ds_read_b128 v[52:55], v62 offset:20480
	v_mov_b32_e32 v32, v29
	s_waitcnt lgkmcnt(1)
	v_mov_b32_e32 v56, v36
	s_waitcnt lgkmcnt(0)
	v_mov_b32_e32 v57, v52
	v_pk_fma_f32 v[14:15], v[100:101], v[56:57], v[14:15] op_sel_hi:[0,1,1]
	ds_read_b128 v[56:59], v62 offset:24576
	ds_read_b128 v[64:67], v62 offset:28672
	v_mov_b32_e32 v52, v37
	s_waitcnt lgkmcnt(1)
	v_mov_b32_e32 v68, v56
	s_waitcnt lgkmcnt(0)
	v_mov_b32_e32 v69, v64
	v_pk_fma_f32 v[12:13], v[100:101], v[68:69], v[12:13] op_sel_hi:[0,1,1]
	ds_read_b128 v[68:71], v62 offset:32768
	v_mov_b32_e32 v64, v57
	s_waitcnt lgkmcnt(0)
	v_fmac_f32_e32 v63, v100, v68
	s_waitcnt vmcnt(14)
	v_pk_fma_f32 v[16:17], v[102:103], v[24:25], v[16:17] op_sel_hi:[0,1,1]
	v_pk_fma_f32 v[18:19], v[102:103], v[32:33], v[18:19] op_sel_hi:[0,1,1]
	v_pk_fma_f32 v[14:15], v[102:103], v[52:53], v[14:15] op_sel_hi:[0,1,1]
	v_pk_fma_f32 v[12:13], v[102:103], v[64:65], v[12:13] op_sel_hi:[0,1,1]
	v_fmac_f32_e32 v63, v102, v69
	v_mov_b32_e32 v24, v22
	s_nop 0
	v_mov_b32_e32 v25, v26
	v_mov_b32_e32 v26, v23
	s_waitcnt vmcnt(13)
	v_pk_fma_f32 v[16:17], v[104:105], v[24:25], v[16:17] op_sel_hi:[0,1,1]
	v_mov_b32_e32 v24, v30
	v_mov_b32_e32 v25, v34
	v_pk_fma_f32 v[18:19], v[104:105], v[24:25], v[18:19] op_sel_hi:[0,1,1]
	v_mov_b32_e32 v24, v38
	v_mov_b32_e32 v25, v54
	v_pk_fma_f32 v[14:15], v[104:105], v[24:25], v[14:15] op_sel_hi:[0,1,1]
	v_mov_b32_e32 v24, v58
	v_mov_b32_e32 v25, v66
	v_pk_fma_f32 v[12:13], v[104:105], v[24:25], v[12:13] op_sel_hi:[0,1,1]
	v_fmac_f32_e32 v63, v104, v70
	v_mov_b32_e32 v54, v39
	s_nop 0
	v_mov_b32_e32 v66, v59
	v_mov_b32_e32 v34, v31
	s_mov_b32 s1, 0x1e000
	s_waitcnt vmcnt(12)
	v_pk_fma_f32 v[20:21], v[106:107], v[26:27], v[16:17] op_sel_hi:[0,1,1]
	v_pk_fma_f32 v[16:17], v[106:107], v[54:55], v[14:15] op_sel_hi:[0,1,1]
	v_pk_fma_f32 v[14:15], v[106:107], v[66:67], v[12:13] op_sel_hi:[0,1,1]
	v_pk_fma_f32 v[18:19], v[106:107], v[34:35], v[18:19] op_sel_hi:[0,1,1]
	s_nop 0
	v_fmac_f32_e32 v63, v106, v71
	ds_read_b128 v[22:25], v62 offset:4112
	v_mov_b32_e32 v26, v8
	s_waitcnt lgkmcnt(0)
	v_mov_b32_e32 v27, v22
	v_mov_b32_e32 v22, v9
	s_waitcnt vmcnt(11)
	v_pk_fma_f32 v[38:39], v[108:109], v[26:27], v[20:21] op_sel_hi:[0,1,1]
	ds_read_b128 v[26:29], v62 offset:8208
	ds_read_b128 v[30:33], v62 offset:12304
	s_waitcnt lgkmcnt(1)
	v_mov_b32_e32 v20, v26
	s_waitcnt lgkmcnt(0)
	v_mov_b32_e32 v21, v30
	v_pk_fma_f32 v[64:65], v[108:109], v[20:21], v[18:19] op_sel_hi:[0,1,1]
	ds_read_b128 v[18:21], v62 offset:16400
	ds_read_b128 v[34:37], v62 offset:20496
	v_mov_b32_e32 v30, v27
	s_waitcnt lgkmcnt(1)
	v_mov_b32_e32 v52, v18
	s_waitcnt lgkmcnt(0)
	v_mov_b32_e32 v53, v34
	v_pk_fma_f32 v[66:67], v[108:109], v[52:53], v[16:17] op_sel_hi:[0,1,1]
	ds_read_b128 v[52:55], v62 offset:24592
	ds_read_b128 v[56:59], v62 offset:28688
	v_mov_b32_e32 v34, v19
	s_waitcnt lgkmcnt(1)
	v_mov_b32_e32 v16, v52
	s_waitcnt lgkmcnt(0)
	v_mov_b32_e32 v17, v56
	v_pk_fma_f32 v[68:69], v[108:109], v[16:17], v[14:15] op_sel_hi:[0,1,1]
	ds_read_b128 v[14:17], v62 offset:32784
	v_mov_b32_e32 v56, v53
	s_waitcnt lgkmcnt(0)
	v_fmac_f32_e32 v63, v108, v14
	v_mov_b32_e32 v14, v10
	s_nop 0
	s_mov_b32 s1, 0x2a000
	s_waitcnt vmcnt(10)
	v_pk_fma_f32 v[12:13], v[110:111], v[22:23], v[38:39] op_sel_hi:[0,1,1]
	v_pk_fma_f32 v[22:23], v[110:111], v[30:31], v[64:65] op_sel_hi:[0,1,1]
	v_pk_fma_f32 v[18:19], v[110:111], v[34:35], v[66:67] op_sel_hi:[0,1,1]
	v_pk_fma_f32 v[26:27], v[110:111], v[56:57], v[68:69] op_sel_hi:[0,1,1]
	v_fmac_f32_e32 v63, v110, v15
	v_mov_b32_e32 v15, v24
	s_nop 0
	v_mov_b32_e32 v24, v11
	s_waitcnt vmcnt(9)
	v_pk_fma_f32 v[12:13], v[112:113], v[14:15], v[12:13] op_sel_hi:[0,1,1]
	v_mov_b32_e32 v14, v28
	v_mov_b32_e32 v15, v32
	v_pk_fma_f32 v[14:15], v[112:113], v[14:15], v[22:23] op_sel_hi:[0,1,1]
	v_mov_b32_e32 v22, v20
	v_mov_b32_e32 v23, v36
	v_pk_fma_f32 v[18:19], v[112:113], v[22:23], v[18:19] op_sel_hi:[0,1,1]
	v_mov_b32_e32 v22, v54
	v_mov_b32_e32 v23, v58
	v_pk_fma_f32 v[22:23], v[112:113], v[22:23], v[26:27] op_sel_hi:[0,1,1]
	v_fmac_f32_e32 v63, v112, v16
	v_mov_b32_e32 v32, v29
	s_nop 0
	v_mov_b32_e32 v36, v21
	v_mov_b32_e32 v58, v55
	s_mov_b32 s1, 0x36000
	s_waitcnt vmcnt(8)
	v_pk_fma_f32 v[12:13], v[114:115], v[24:25], v[12:13] op_sel_hi:[0,1,1]
	v_pk_fma_f32 v[24:25], v[114:115], v[32:33], v[14:15] op_sel_hi:[0,1,1]
	v_pk_fma_f32 v[28:29], v[114:115], v[36:37], v[18:19] op_sel_hi:[0,1,1]
	v_pk_fma_f32 v[36:37], v[114:115], v[58:59], v[22:23] op_sel_hi:[0,1,1]
	v_fmac_f32_e32 v63, v114, v17
	v_mov_b32_e32 v14, v4
	s_nop 0
	ds_read_b128 v[8:11], v62 offset:4128
	s_waitcnt lgkmcnt(0)
	v_mov_b32_e32 v15, v8
	v_mov_b32_e32 v8, v5
	s_waitcnt vmcnt(7)
	v_pk_fma_f32 v[52:53], v[116:117], v[14:15], v[12:13] op_sel_hi:[0,1,1]
	ds_read_b128 v[12:15], v62 offset:8224
	ds_read_b128 v[16:19], v62 offset:12320
	s_waitcnt lgkmcnt(1)
	v_mov_b32_e32 v20, v12
	s_waitcnt lgkmcnt(0)
	v_mov_b32_e32 v21, v16
	v_pk_fma_f32 v[54:55], v[116:117], v[20:21], v[24:25] op_sel_hi:[0,1,1]
	ds_read_b128 v[20:23], v62 offset:16416
	ds_read_b128 v[24:27], v62 offset:20512
	v_mov_b32_e32 v16, v13
	s_waitcnt lgkmcnt(1)
	v_mov_b32_e32 v30, v20
	s_waitcnt lgkmcnt(0)
	v_mov_b32_e32 v31, v24
	v_pk_fma_f32 v[56:57], v[116:117], v[30:31], v[28:29] op_sel_hi:[0,1,1]
	ds_read_b128 v[28:31], v62 offset:24608
	ds_read_b128 v[32:35], v62 offset:28704
	v_mov_b32_e32 v24, v21
	s_waitcnt lgkmcnt(1)
	v_mov_b32_e32 v38, v28
	s_waitcnt lgkmcnt(0)
	v_mov_b32_e32 v39, v32
	v_pk_fma_f32 v[58:59], v[116:117], v[38:39], v[36:37] op_sel_hi:[0,1,1]
	ds_read_b128 v[36:39], v62 offset:32800
	v_mov_b32_e32 v32, v29
	s_waitcnt lgkmcnt(0)
	v_fmac_f32_e32 v63, v116, v36
	s_mov_b32 s1, 0x42000
	s_nop 0
	s_waitcnt vmcnt(6)
	v_pk_fma_f32 v[8:9], v[118:119], v[8:9], v[52:53] op_sel_hi:[0,1,1]
	v_pk_fma_f32 v[12:13], v[118:119], v[16:17], v[54:55] op_sel_hi:[0,1,1]
	v_pk_fma_f32 v[16:17], v[118:119], v[24:25], v[56:57] op_sel_hi:[0,1,1]
	v_pk_fma_f32 v[20:21], v[118:119], v[32:33], v[58:59] op_sel_hi:[0,1,1]
	v_fmac_f32_e32 v63, v118, v37
	v_mov_b32_e32 v24, v6
	s_nop 0
	v_mov_b32_e32 v25, v10
	v_mov_b32_e32 v10, v7
	s_waitcnt vmcnt(5)
	v_pk_fma_f32 v[8:9], v[120:121], v[24:25], v[8:9] op_sel_hi:[0,1,1]
	v_mov_b32_e32 v24, v14
	v_mov_b32_e32 v25, v18
	v_pk_fma_f32 v[24:25], v[120:121], v[24:25], v[12:13] op_sel_hi:[0,1,1]
	v_mov_b32_e32 v12, v22
	v_mov_b32_e32 v13, v26
	v_pk_fma_f32 v[16:17], v[120:121], v[12:13], v[16:17] op_sel_hi:[0,1,1]
	v_mov_b32_e32 v12, v30
	v_mov_b32_e32 v13, v34
	v_pk_fma_f32 v[20:21], v[120:121], v[12:13], v[20:21] op_sel_hi:[0,1,1]
	v_fmac_f32_e32 v63, v120, v38
	v_mov_b32_e32 v18, v15
	s_nop 0
	v_mov_b32_e32 v26, v23
	v_mov_b32_e32 v34, v31
	s_mov_b32 s1, 0x48000
	s_waitcnt vmcnt(4)
	v_pk_fma_f32 v[12:13], v[122:123], v[10:11], v[8:9] op_sel_hi:[0,1,1]
	v_pk_fma_f32 v[10:11], v[122:123], v[18:19], v[24:25] op_sel_hi:[0,1,1]
	v_pk_fma_f32 v[8:9], v[122:123], v[26:27], v[16:17] op_sel_hi:[0,1,1]
	v_pk_fma_f32 v[4:5], v[122:123], v[34:35], v[20:21] op_sel_hi:[0,1,1]
	v_fmac_f32_e32 v63, v122, v39
	ds_read_b128 v[14:17], v62 offset:4144
	s_nop 0
	v_mov_b32_e32 v18, v0
	s_waitcnt lgkmcnt(0)
	v_mov_b32_e32 v19, v14
	s_mov_b32 s1, 0x4e000
	v_mov_b32_e32 v14, v1
	s_waitcnt vmcnt(3)
	v_pk_fma_f32 v[38:39], v[124:125], v[18:19], v[12:13] op_sel_hi:[0,1,1]
	ds_read_b128 v[18:21], v62 offset:8240
	ds_read_b128 v[22:25], v62 offset:12336
	s_waitcnt lgkmcnt(1)
	v_mov_b32_e32 v12, v18
	s_waitcnt lgkmcnt(0)
	v_mov_b32_e32 v13, v22
	v_pk_fma_f32 v[56:57], v[124:125], v[12:13], v[10:11] op_sel_hi:[0,1,1]
	ds_read_b128 v[10:13], v62 offset:16432
	ds_read_b128 v[26:29], v62 offset:20528
	v_mov_b32_e32 v22, v19
	s_waitcnt lgkmcnt(1)
	v_mov_b32_e32 v30, v10
	s_waitcnt lgkmcnt(0)
	v_mov_b32_e32 v31, v26
	v_pk_fma_f32 v[8:9], v[124:125], v[30:31], v[8:9] op_sel_hi:[0,1,1]
	ds_read_b128 v[30:33], v62 offset:24624
	ds_read_b128 v[34:37], v62 offset:28720
	v_mov_b32_e32 v26, v11
	v_mov_b32_e32 v10, v2
	v_mov_b32_e32 v11, v16
	s_waitcnt lgkmcnt(1)
	v_mov_b32_e32 v52, v30
	s_waitcnt lgkmcnt(0)
	v_mov_b32_e32 v53, v34
	v_pk_fma_f32 v[4:5], v[124:125], v[52:53], v[4:5] op_sel_hi:[0,1,1]
	ds_read_b128 v[52:55], v62 offset:32816
	v_mov_b32_e32 v34, v31
	v_mov_b32_e32 v16, v3
	v_add_u32_e32 v62, 64, v62
	s_waitcnt lgkmcnt(0)
	v_fmac_f32_e32 v63, v124, v52
	s_mov_b32 s1, 0x54000
	s_nop 0
	s_waitcnt vmcnt(2)
	v_pk_fma_f32 v[6:7], v[126:127], v[14:15], v[38:39] op_sel_hi:[0,1,1]
	v_pk_fma_f32 v[14:15], v[126:127], v[22:23], v[56:57] op_sel_hi:[0,1,1]
	v_pk_fma_f32 v[8:9], v[126:127], v[26:27], v[8:9] op_sel_hi:[0,1,1]
	v_pk_fma_f32 v[4:5], v[126:127], v[34:35], v[4:5] op_sel_hi:[0,1,1]
	v_fmac_f32_e32 v63, v126, v53
	s_mov_b32 s1, 0x5a000
	s_nop 0
	s_waitcnt vmcnt(1)
	v_pk_fma_f32 v[6:7], v[128:129], v[10:11], v[6:7] op_sel_hi:[0,1,1]
	v_mov_b32_e32 v10, v20
	v_mov_b32_e32 v11, v24
	v_pk_fma_f32 v[10:11], v[128:129], v[10:11], v[14:15] op_sel_hi:[0,1,1]
	v_mov_b32_e32 v14, v12
	v_mov_b32_e32 v15, v28
	v_pk_fma_f32 v[8:9], v[128:129], v[14:15], v[8:9] op_sel_hi:[0,1,1]
	v_mov_b32_e32 v14, v32
	v_mov_b32_e32 v15, v36
	v_pk_fma_f32 v[4:5], v[128:129], v[14:15], v[4:5] op_sel_hi:[0,1,1]
	v_fmac_f32_e32 v63, v128, v54
	v_mov_b32_e32 v24, v21
	s_nop 0
	v_mov_b32_e32 v28, v13
	v_mov_b32_e32 v36, v33
	s_waitcnt vmcnt(0)
	v_pk_fma_f32 v[16:17], v[130:131], v[16:17], v[6:7] op_sel_hi:[0,1,1]
	v_pk_fma_f32 v[18:19], v[130:131], v[24:25], v[10:11] op_sel_hi:[0,1,1]
	v_pk_fma_f32 v[14:15], v[130:131], v[28:29], v[8:9] op_sel_hi:[0,1,1]
	v_pk_fma_f32 v[12:13], v[130:131], v[36:37], v[4:5] op_sel_hi:[0,1,1]
	v_fmac_f32_e32 v63, v130, v55
	s_cbranch_scc1 .LBB0_1228
	v_add_u32_e32 v0, 0x9000, v60
	ds_write2_b32 v0, v16, v17 offset1:32
	ds_write2_b32 v0, v18, v19 offset0:64 offset1:96
	ds_write2_b32 v0, v14, v15 offset0:128 offset1:160
	ds_write2_b32 v0, v12, v13 offset0:192 offset1:224
	ds_write_b32 v60, v63 offset:37888
	s_waitcnt lgkmcnt(0)
	s_barrier
	s_and_saveexec_b64 s[6:7], s[38:39]
	s_cbranch_execz .LBB0_1226
	v_readlane_b32 s10, v252, 37
	v_readlane_b32 s11, v252, 38
	s_andn2_b64 vcc, exec, s[10:11]
	s_cbranch_vccz .LBB0_1224
	v_mov_b32_e32 v0, 0
	s_branch .LBB0_1225
